# grid barrier: non-leader workgroups poll the cross-XCD release generation directly (skip the per-XCD relay hop); same acquire/invalidate per workgroup
# baseline (speedup 1.0000x reference)
; __device__ __forceinline__ unsigned xb_ld(unsigned* p)              { return __hip_atomic_load(p, __ATOMIC_RELAXED, __HIP_MEMORY_SCOPE_AGENT); }
; __device__ __forceinline__ unsigned xb_add(unsigned* p, unsigned v) { return __hip_atomic_fetch_add(p, v, __ATOMIC_RELAXED, __HIP_MEMORY_SCOPE_AGENT); }
; #define XB_SPIN(cond, bar) do { unsigned _sp = 0; while (cond) { __builtin_amdgcn_s_sleep(1); \
;     if ((++_sp & 255u) == 0u) { if (xb_ld(&(bar)[XB_TMO])) break; if (_sp > XB_SPIN_CAP) { atomicAdd(&(bar)[XB_TMO], 1u); break; } } } } while (0)
; __device__ __forceinline__ void xcd_barrier(const XcdBarrier& b) {
;     ...
;         const unsigned old = xb_add(&bar[XB_XSUB(b.x)], 1u);
;         const unsigned gen = old / nloc;
;         if (old + 1u == (gen + 1u) * nloc) {
;             __builtin_amdgcn_fence(__ATOMIC_RELEASE, "agent");
;             asm volatile("s_waitcnt vmcnt(0)" ::: "memory");
;             const unsigned og = xb_add(&bar[XB_TOP], 1u);
;             const unsigned tg = og / nx;
;             if (og + 1u == (tg + 1u) * nx) xb_add(&bar[XB_TOPGEN], 1u);
;             else XB_SPIN(xb_ld(&bar[XB_TOPGEN]) == tg, bar);
;             __builtin_amdgcn_fence(__ATOMIC_ACQUIRE, "agent");
;             xb_add(&bar[XB_XGEN(b.x)], 1u);
;             asm volatile("s_waitcnt vmcnt(0)" ::: "memory");
;         } else {
;             XB_SPIN(xb_ld(&bar[XB_XGEN(b.x)]) == gen, bar);
.LBB0_364:
	s_or_b64 exec, exec, s[2:3]
	v_cvt_f32_u32_e32 v5, v3
	s_waitcnt vmcnt(0)
	v_readfirstlane_b32 s2, v4
	v_sub_u32_e32 v4, 0, v3
	v_rcp_iflag_f32_e32 v5, v5
	v_add_u32_e32 v6, s2, v2
	v_mul_f32_e32 v5, 0x4f7ffffe, v5
	v_cvt_u32_f32_e32 v5, v5
	v_mul_lo_u32 v2, v4, v5
	v_mul_hi_u32 v2, v5, v2
	v_add_u32_e32 v2, v5, v2
	v_mul_hi_u32 v2, v6, v2
	v_mul_lo_u32 v4, v2, v3
	v_sub_u32_e32 v4, v6, v4
	v_add_u32_e32 v5, 1, v2
	v_cmp_ge_u32_e32 vcc, v4, v3
	s_nop 1
	v_cndmask_b32_e32 v2, v2, v5, vcc
	v_sub_u32_e32 v5, v4, v3
	v_cndmask_b32_e32 v4, v4, v5, vcc
	v_add_u32_e32 v5, 1, v2
	v_cmp_ge_u32_e32 vcc, v4, v3
	v_add_u32_e32 v4, 1, v6
	s_nop 0
	v_cndmask_b32_e32 v2, v2, v5, vcc
	v_mul_lo_u32 v5, v3, v2
	v_add_u32_e32 v3, v5, v3
	v_cmp_ne_u32_e32 vcc, v4, v3
	s_and_saveexec_b64 s[2:3], vcc
	s_xor_b64 s[2:3], exec, s[2:3]
	s_cbranch_execz .LBB0_378
	v_readlane_b32 s4, v255, 17
	s_waitcnt lgkmcnt(0)
	v_mov_b32_e32 v1, 0
	v_readlane_b32 s5, v255, 18
	s_nop 4
	global_load_dword v3, v1, s[4:5] sc1
	s_waitcnt vmcnt(0)
	v_cmp_eq_u32_e32 vcc, v3, v2
	s_and_saveexec_b64 s[14:15], vcc
	s_cbranch_execz .LBB0_377
	s_mov_b32 s4, 1
	s_mov_b64 s[18:19], 0
	s_branch .LBB0_368

; __device__ __forceinline__ unsigned xb_ld(unsigned* p)              { return __hip_atomic_load(p, __ATOMIC_RELAXED, __HIP_MEMORY_SCOPE_AGENT); }
; #define XB_SPIN(cond, bar) do { unsigned _sp = 0; while (cond) { __builtin_amdgcn_s_sleep(1); \
;     if ((++_sp & 255u) == 0u) { if (xb_ld(&(bar)[XB_TMO])) break; if (_sp > XB_SPIN_CAP) { atomicAdd(&(bar)[XB_TMO], 1u); break; } } } } while (0)
; __device__ __forceinline__ void xcd_barrier(const XcdBarrier& b) {
;     ...
;             XB_SPIN(xb_ld(&bar[XB_XGEN(b.x)]) == gen, bar);
.LBB0_370:
	v_readlane_b32 s6, v255, 17
	v_readlane_b32 s7, v255, 18
	s_add_i32 s4, s4, 1
	s_mov_b64 s[24:25], -1
	s_nop 2
	global_load_dword v3, v1, s[6:7] sc1
	s_waitcnt vmcnt(0)
	v_cmp_ne_u32_e32 vcc, v3, v2
	s_orn2_b64 s[22:23], vcc, exec
	s_branch .LBB0_367

; __device__ __forceinline__ unsigned xb_ld(unsigned* p)              { return __hip_atomic_load(p, __ATOMIC_RELAXED, __HIP_MEMORY_SCOPE_AGENT); }
; __device__ __forceinline__ unsigned xb_add(unsigned* p, unsigned v) { return __hip_atomic_fetch_add(p, v, __ATOMIC_RELAXED, __HIP_MEMORY_SCOPE_AGENT); }
; #define XB_SPIN(cond, bar) do { unsigned _sp = 0; while (cond) { __builtin_amdgcn_s_sleep(1); \
;     if ((++_sp & 255u) == 0u) { if (xb_ld(&(bar)[XB_TMO])) break; if (_sp > XB_SPIN_CAP) { atomicAdd(&(bar)[XB_TMO], 1u); break; } } } } while (0)
; __device__ __forceinline__ void xcd_barrier(const XcdBarrier& b) {
;     ...
;         const unsigned old = xb_add(&bar[XB_XSUB(b.x)], 1u);
;         const unsigned gen = old / nloc;
;         if (old + 1u == (gen + 1u) * nloc) {
;             __builtin_amdgcn_fence(__ATOMIC_RELEASE, "agent");
;             asm volatile("s_waitcnt vmcnt(0)" ::: "memory");
;             const unsigned og = xb_add(&bar[XB_TOP], 1u);
;             const unsigned tg = og / nx;
;             if (og + 1u == (tg + 1u) * nx) xb_add(&bar[XB_TOPGEN], 1u);
;             else XB_SPIN(xb_ld(&bar[XB_TOPGEN]) == tg, bar);
;             __builtin_amdgcn_fence(__ATOMIC_ACQUIRE, "agent");
;             xb_add(&bar[XB_XGEN(b.x)], 1u);
;             asm volatile("s_waitcnt vmcnt(0)" ::: "memory");
;         } else {
;             XB_SPIN(xb_ld(&bar[XB_XGEN(b.x)]) == gen, bar);
.LBB0_634:
	s_or_b64 exec, exec, s[26:27]
	v_cvt_f32_u32_e32 v6, v4
	s_waitcnt vmcnt(0)
	v_readfirstlane_b32 s8, v5
	v_sub_u32_e32 v5, 0, v4
	v_rcp_iflag_f32_e32 v6, v6
	v_add_u32_e32 v7, s8, v3
	v_mul_f32_e32 v6, 0x4f7ffffe, v6
	v_cvt_u32_f32_e32 v6, v6
	v_mul_lo_u32 v3, v5, v6
	v_mul_hi_u32 v3, v6, v3
	v_add_u32_e32 v3, v6, v3
	v_mul_hi_u32 v3, v7, v3
	v_mul_lo_u32 v5, v3, v4
	v_sub_u32_e32 v5, v7, v5
	v_add_u32_e32 v6, 1, v3
	v_cmp_ge_u32_e32 vcc, v5, v4
	s_nop 1
	v_cndmask_b32_e32 v3, v3, v6, vcc
	v_sub_u32_e32 v6, v5, v4
	v_cndmask_b32_e32 v5, v5, v6, vcc
	v_add_u32_e32 v6, 1, v3
	v_cmp_ge_u32_e32 vcc, v5, v4
	v_add_u32_e32 v5, 1, v7
	s_nop 0
	v_cndmask_b32_e32 v3, v3, v6, vcc
	v_mul_lo_u32 v6, v4, v3
	v_add_u32_e32 v4, v6, v4
	v_cmp_ne_u32_e32 vcc, v5, v4
	s_and_saveexec_b64 s[8:9], vcc
	s_xor_b64 s[26:27], exec, s[8:9]
	s_cbranch_execz .LBB0_648
	v_readlane_b32 s8, v255, 17
	v_readlane_b32 s9, v255, 18
	s_waitcnt lgkmcnt(0)
	s_nop 3
	global_load_dword v2, v35, s[8:9] sc1
	s_waitcnt vmcnt(0)
	v_cmp_eq_u32_e32 vcc, v2, v3
	s_and_saveexec_b64 s[28:29], vcc
	s_cbranch_execz .LBB0_647
	s_mov_b32 s8, 1
	s_mov_b64 s[30:31], 0
	s_branch .LBB0_638

; __device__ __forceinline__ unsigned xb_ld(unsigned* p)              { return __hip_atomic_load(p, __ATOMIC_RELAXED, __HIP_MEMORY_SCOPE_AGENT); }
; #define XB_SPIN(cond, bar) do { unsigned _sp = 0; while (cond) { __builtin_amdgcn_s_sleep(1); \
;     if ((++_sp & 255u) == 0u) { if (xb_ld(&(bar)[XB_TMO])) break; if (_sp > XB_SPIN_CAP) { atomicAdd(&(bar)[XB_TMO], 1u); break; } } } } while (0)
; __device__ __forceinline__ void xcd_barrier(const XcdBarrier& b) {
;     ...
;             XB_SPIN(xb_ld(&bar[XB_XGEN(b.x)]) == gen, bar);
.LBB0_640:
	v_readlane_b32 s10, v255, 17
	v_readlane_b32 s11, v255, 18
	s_add_i32 s8, s8, 1
	s_mov_b64 s[40:41], -1
	s_nop 2
	global_load_dword v2, v35, s[10:11] sc1
	s_waitcnt vmcnt(0)
	v_cmp_ne_u32_e32 vcc, v2, v3
	s_orn2_b64 s[38:39], vcc, exec
	s_branch .LBB0_637

; __device__ __forceinline__ unsigned xb_ld(unsigned* p)              { return __hip_atomic_load(p, __ATOMIC_RELAXED, __HIP_MEMORY_SCOPE_AGENT); }
; __device__ __forceinline__ unsigned xb_add(unsigned* p, unsigned v) { return __hip_atomic_fetch_add(p, v, __ATOMIC_RELAXED, __HIP_MEMORY_SCOPE_AGENT); }
; #define XB_SPIN(cond, bar) do { unsigned _sp = 0; while (cond) { __builtin_amdgcn_s_sleep(1); \
;     if ((++_sp & 255u) == 0u) { if (xb_ld(&(bar)[XB_TMO])) break; if (_sp > XB_SPIN_CAP) { atomicAdd(&(bar)[XB_TMO], 1u); break; } } } } while (0)
; __device__ __forceinline__ void xcd_barrier(const XcdBarrier& b) {
;     ...
;         const unsigned old = xb_add(&bar[XB_XSUB(b.x)], 1u);
;         const unsigned gen = old / nloc;
;         if (old + 1u == (gen + 1u) * nloc) {
;             __builtin_amdgcn_fence(__ATOMIC_RELEASE, "agent");
;             asm volatile("s_waitcnt vmcnt(0)" ::: "memory");
;             const unsigned og = xb_add(&bar[XB_TOP], 1u);
;             const unsigned tg = og / nx;
;             if (og + 1u == (tg + 1u) * nx) xb_add(&bar[XB_TOPGEN], 1u);
;             else XB_SPIN(xb_ld(&bar[XB_TOPGEN]) == tg, bar);
;             __builtin_amdgcn_fence(__ATOMIC_ACQUIRE, "agent");
;             xb_add(&bar[XB_XGEN(b.x)], 1u);
;             asm volatile("s_waitcnt vmcnt(0)" ::: "memory");
;         } else {
;             XB_SPIN(xb_ld(&bar[XB_XGEN(b.x)]) == gen, bar);
.LBB0_872:
	s_or_b64 exec, exec, s[26:27]
	v_cvt_f32_u32_e32 v6, v4
	s_waitcnt vmcnt(0)
	v_readfirstlane_b32 s7, v5
	v_sub_u32_e32 v5, 0, v4
	v_rcp_iflag_f32_e32 v6, v6
	v_add_u32_e32 v7, s7, v3
	v_mul_f32_e32 v6, 0x4f7ffffe, v6
	v_cvt_u32_f32_e32 v6, v6
	v_mul_lo_u32 v3, v5, v6
	v_mul_hi_u32 v3, v6, v3
	v_add_u32_e32 v3, v6, v3
	v_mul_hi_u32 v3, v7, v3
	v_mul_lo_u32 v5, v3, v4
	v_sub_u32_e32 v5, v7, v5
	v_add_u32_e32 v6, 1, v3
	v_cmp_ge_u32_e32 vcc, v5, v4
	s_nop 1
	v_cndmask_b32_e32 v3, v3, v6, vcc
	v_sub_u32_e32 v6, v5, v4
	v_cndmask_b32_e32 v5, v5, v6, vcc
	v_add_u32_e32 v6, 1, v3
	v_cmp_ge_u32_e32 vcc, v5, v4
	v_add_u32_e32 v5, 1, v7
	s_nop 0
	v_cndmask_b32_e32 v3, v3, v6, vcc
	v_mul_lo_u32 v6, v4, v3
	v_add_u32_e32 v4, v6, v4
	v_cmp_ne_u32_e32 vcc, v5, v4
	s_and_saveexec_b64 s[8:9], vcc
	s_xor_b64 s[26:27], exec, s[8:9]
	s_cbranch_execz .LBB0_886
	v_readlane_b32 s8, v255, 17
	v_readlane_b32 s9, v255, 18
	s_waitcnt lgkmcnt(0)
	s_nop 3
	global_load_dword v2, v35, s[8:9] sc1
	s_waitcnt vmcnt(0)
	v_cmp_eq_u32_e32 vcc, v2, v3
	s_and_saveexec_b64 s[28:29], vcc
	s_cbranch_execz .LBB0_885
	s_mov_b32 s7, 1
	s_mov_b64 s[30:31], 0
	s_branch .LBB0_876

; __device__ __forceinline__ unsigned xb_ld(unsigned* p)              { return __hip_atomic_load(p, __ATOMIC_RELAXED, __HIP_MEMORY_SCOPE_AGENT); }
; #define XB_SPIN(cond, bar) do { unsigned _sp = 0; while (cond) { __builtin_amdgcn_s_sleep(1); \
;     if ((++_sp & 255u) == 0u) { if (xb_ld(&(bar)[XB_TMO])) break; if (_sp > XB_SPIN_CAP) { atomicAdd(&(bar)[XB_TMO], 1u); break; } } } } while (0)
; __device__ __forceinline__ void xcd_barrier(const XcdBarrier& b) {
;     ...
;             XB_SPIN(xb_ld(&bar[XB_XGEN(b.x)]) == gen, bar);
.LBB0_878:
	v_readlane_b32 s8, v255, 17
	v_readlane_b32 s9, v255, 18
	s_add_i32 s7, s7, 1
	s_mov_b64 s[40:41], -1
	s_nop 2
	global_load_dword v2, v35, s[8:9] sc1
	s_waitcnt vmcnt(0)
	v_cmp_ne_u32_e32 vcc, v2, v3
	s_orn2_b64 s[38:39], vcc, exec
	s_branch .LBB0_875

; __device__ __forceinline__ unsigned xb_ld(unsigned* p)              { return __hip_atomic_load(p, __ATOMIC_RELAXED, __HIP_MEMORY_SCOPE_AGENT); }
; __device__ __forceinline__ unsigned xb_add(unsigned* p, unsigned v) { return __hip_atomic_fetch_add(p, v, __ATOMIC_RELAXED, __HIP_MEMORY_SCOPE_AGENT); }
; #define XB_SPIN(cond, bar) do { unsigned _sp = 0; while (cond) { __builtin_amdgcn_s_sleep(1); \
;     if ((++_sp & 255u) == 0u) { if (xb_ld(&(bar)[XB_TMO])) break; if (_sp > XB_SPIN_CAP) { atomicAdd(&(bar)[XB_TMO], 1u); break; } } } } while (0)
; __device__ __forceinline__ void xcd_barrier(const XcdBarrier& b) {
;     ...
;         const unsigned old = xb_add(&bar[XB_XSUB(b.x)], 1u);
;         const unsigned gen = old / nloc;
;         if (old + 1u == (gen + 1u) * nloc) {
;             __builtin_amdgcn_fence(__ATOMIC_RELEASE, "agent");
;             asm volatile("s_waitcnt vmcnt(0)" ::: "memory");
;             const unsigned og = xb_add(&bar[XB_TOP], 1u);
;             const unsigned tg = og / nx;
;             if (og + 1u == (tg + 1u) * nx) xb_add(&bar[XB_TOPGEN], 1u);
;             else XB_SPIN(xb_ld(&bar[XB_TOPGEN]) == tg, bar);
;             __builtin_amdgcn_fence(__ATOMIC_ACQUIRE, "agent");
;             xb_add(&bar[XB_XGEN(b.x)], 1u);
;             asm volatile("s_waitcnt vmcnt(0)" ::: "memory");
;         } else {
;             XB_SPIN(xb_ld(&bar[XB_XGEN(b.x)]) == gen, bar);
.LBB0_1693:
	s_or_b64 exec, exec, s[26:27]
	v_cvt_f32_u32_e32 v6, v4
	s_waitcnt vmcnt(0)
	v_readfirstlane_b32 s6, v5
	v_sub_u32_e32 v5, 0, v4
	v_rcp_iflag_f32_e32 v6, v6
	v_add_u32_e32 v7, s6, v3
	v_mul_f32_e32 v6, 0x4f7ffffe, v6
	v_cvt_u32_f32_e32 v6, v6
	v_mul_lo_u32 v3, v5, v6
	v_mul_hi_u32 v3, v6, v3
	v_add_u32_e32 v3, v6, v3
	v_mul_hi_u32 v3, v7, v3
	v_mul_lo_u32 v5, v3, v4
	v_sub_u32_e32 v5, v7, v5
	v_add_u32_e32 v6, 1, v3
	v_cmp_ge_u32_e32 vcc, v5, v4
	s_nop 1
	v_cndmask_b32_e32 v3, v3, v6, vcc
	v_sub_u32_e32 v6, v5, v4
	v_cndmask_b32_e32 v5, v5, v6, vcc
	v_add_u32_e32 v6, 1, v3
	v_cmp_ge_u32_e32 vcc, v5, v4
	v_add_u32_e32 v5, 1, v7
	s_nop 0
	v_cndmask_b32_e32 v3, v3, v6, vcc
	v_mul_lo_u32 v6, v4, v3
	v_add_u32_e32 v4, v6, v4
	v_cmp_ne_u32_e32 vcc, v5, v4
	s_and_saveexec_b64 s[8:9], vcc
	s_xor_b64 s[26:27], exec, s[8:9]
	s_cbranch_execz .LBB0_1707
	v_readlane_b32 s8, v255, 17
	v_readlane_b32 s9, v255, 18
	s_waitcnt lgkmcnt(0)
	s_nop 3
	global_load_dword v2, v35, s[8:9] sc1
	s_waitcnt vmcnt(0)
	v_cmp_eq_u32_e32 vcc, v2, v3
	s_and_saveexec_b64 s[28:29], vcc
	s_cbranch_execz .LBB0_1706
	s_mov_b32 s6, 1
	s_mov_b64 s[30:31], 0
	s_branch .LBB0_1697

; __device__ __forceinline__ unsigned xb_ld(unsigned* p)              { return __hip_atomic_load(p, __ATOMIC_RELAXED, __HIP_MEMORY_SCOPE_AGENT); }
; #define XB_SPIN(cond, bar) do { unsigned _sp = 0; while (cond) { __builtin_amdgcn_s_sleep(1); \
;     if ((++_sp & 255u) == 0u) { if (xb_ld(&(bar)[XB_TMO])) break; if (_sp > XB_SPIN_CAP) { atomicAdd(&(bar)[XB_TMO], 1u); break; } } } } while (0)
; __device__ __forceinline__ void xcd_barrier(const XcdBarrier& b) {
;     ...
;             XB_SPIN(xb_ld(&bar[XB_XGEN(b.x)]) == gen, bar);
.LBB0_1699:
	v_readlane_b32 s8, v255, 17
	v_readlane_b32 s9, v255, 18
	s_add_i32 s6, s6, 1
	s_mov_b64 s[40:41], -1
	s_nop 2
	global_load_dword v2, v35, s[8:9] sc1
	s_waitcnt vmcnt(0)
	v_cmp_ne_u32_e32 vcc, v2, v3
	s_orn2_b64 s[38:39], vcc, exec
	s_branch .LBB0_1696
